# P2 gate loads as 6 dwordx4 + permlane16 swaps (instead of 12 dwordx2)
# speedup vs baseline: 1.0354x; 1.0067x over previous
.LBB0_208:
	s_or_b64 exec, exec, s[0:1]
	v_readlane_b32 s0, v255, 19
	v_readlane_b32 s1, v255, 20
	s_and_b64 s[0:1], s[0:1], exec
	s_cselect_b32 s0, s96, s41
	s_lshl_b32 s0, s0, 7
	s_or_b32 s13, s0, s79
	v_add_u32_e32 v0, 0, v91
	v_or_b32_e32 v1, s13, v101
	s_waitcnt lgkmcnt(0)
	v_mad_u32_u24 v1, v1, s61, v0
	ds_read_b128 v[74:77], v1
	ds_read_b128 v[78:81], v1 offset:64
	s_and_b64 s[0:1], s[98:99], exec
	s_cselect_b32 s0, s96, s41
	s_lshl_b32 s14, s0, 7
	s_waitcnt vmcnt(11) lgkmcnt(1)
	v_mfma_f32_16x16x32_bf16 v[74:77], v[74:77], v[44:47], 0
	s_or_b32 s0, s77, s14
	v_or_b32_e32 v1, s0, v101
	s_and_b64 s[0:1], s[4:5], exec
	v_mad_u32_u24 v1, v1, s61, v0
	s_cselect_b32 s0, s96, s41
	s_waitcnt vmcnt(10) lgkmcnt(0)
	v_mfma_f32_16x16x32_bf16 v[74:77], v[78:81], v[40:43], v[74:77]
	ds_read_b128 v[78:81], v1
	ds_read_b128 v[82:85], v1 offset:64
	s_lshl_b32 s0, s0, 7
	s_or_b32 s11, s0, s36
	v_or_b32_e32 v1, s11, v101
	v_mad_u32_u24 v1, v1, s61, v0
	s_waitcnt lgkmcnt(1)
	v_mfma_f32_16x16x32_bf16 v[78:81], v[78:81], v[44:47], 0
	ds_read_b128 v[86:89], v1
	s_and_b64 s[0:1], s[26:27], exec
	s_cselect_b32 s0, s96, s41
	s_waitcnt lgkmcnt(1)
	v_mfma_f32_16x16x32_bf16 v[78:81], v[82:85], v[40:43], v[78:81]
	ds_read_b128 v[82:85], v1 offset:64
	s_lshl_b32 s12, s0, 7
	s_or_b32 s0, s72, s12
	s_waitcnt lgkmcnt(1)
	v_mfma_f32_16x16x32_bf16 v[86:89], v[86:89], v[44:47], 0
	v_or_b32_e32 v1, s0, v101
	s_and_b64 s[0:1], s[24:25], exec
	v_mad_u32_u24 v1, v1, s61, v0
	s_cselect_b32 s0, s96, s41
	s_waitcnt lgkmcnt(0)
	v_mfma_f32_16x16x32_bf16 v[82:85], v[82:85], v[40:43], v[86:89]
	s_nop 2
	ds_read_b128 v[86:89], v1
	ds_read_b128 v[106:109], v1 offset:64
	s_lshl_b32 s0, s0, 7
	s_or_b32 s9, s0, s43
	v_or_b32_e32 v1, s9, v101
	v_mad_u32_u24 v1, v1, s61, v0
	s_waitcnt lgkmcnt(1)
	v_mfma_f32_16x16x32_bf16 v[86:89], v[86:89], v[44:47], 0
	ds_read_b128 v[110:113], v1
	s_and_b64 s[0:1], s[28:29], exec
	s_cselect_b32 s0, s96, s41
	s_waitcnt lgkmcnt(1)
	v_mfma_f32_16x16x32_bf16 v[86:89], v[106:109], v[40:43], v[86:89]
	ds_read_b128 v[106:109], v1 offset:64
	s_lshl_b32 s10, s0, 7
	s_or_b32 s0, s47, s10
	s_waitcnt lgkmcnt(1)
	v_mfma_f32_16x16x32_bf16 v[110:113], v[110:113], v[44:47], 0
	v_or_b32_e32 v1, s0, v101
	s_and_b64 s[0:1], s[2:3], exec
	v_mad_u32_u24 v1, v1, s61, v0
	s_cselect_b32 s0, s96, s41
	s_waitcnt lgkmcnt(0)
	v_mfma_f32_16x16x32_bf16 v[106:109], v[106:109], v[40:43], v[110:113]
	s_nop 2
	ds_read_b128 v[110:113], v1
	ds_read_b128 v[114:117], v1 offset:64
	s_lshl_b32 s0, s0, 7
	s_or_b32 s7, s0, s49
	v_or_b32_e32 v1, s7, v101
	v_mad_u32_u24 v1, v1, s61, v0
	s_waitcnt lgkmcnt(1)
	v_mfma_f32_16x16x32_bf16 v[110:113], v[110:113], v[44:47], 0
	ds_read_b128 v[118:121], v1
	s_and_b64 s[0:1], s[30:31], exec
	s_cselect_b32 s0, s96, s41
	s_waitcnt lgkmcnt(1)
	v_mfma_f32_16x16x32_bf16 v[110:113], v[114:117], v[40:43], v[110:113]
	ds_read_b128 v[114:117], v1 offset:64
	s_lshl_b32 s8, s0, 7
	s_or_b32 s0, s76, s8
	s_waitcnt lgkmcnt(1)
	v_mfma_f32_16x16x32_bf16 v[118:121], v[118:121], v[44:47], 0
	v_or_b32_e32 v1, s0, v101
	s_and_b64 s[0:1], s[80:81], exec
	v_mad_u32_u24 v1, v1, s61, v0
	s_cselect_b32 s0, s96, s41
	s_waitcnt lgkmcnt(0)
	v_mfma_f32_16x16x32_bf16 v[114:117], v[114:117], v[40:43], v[118:121]
	s_nop 2
	ds_read_b128 v[118:121], v1
	ds_read_b128 v[122:125], v1 offset:64
	s_lshl_b32 s0, s0, 7
	s_or_b32 s6, s0, s73
	v_or_b32_e32 v1, s6, v101
	v_mad_u32_u24 v0, v1, s61, v0
	s_waitcnt lgkmcnt(1)
	v_mfma_f32_16x16x32_bf16 v[118:121], v[118:121], v[44:47], 0
	ds_read_b128 v[126:129], v0
	s_cmp_lg_u32 s54, 0
	s_cselect_b64 s[0:1], -1, 0
	s_waitcnt lgkmcnt(1)
	v_mfma_f32_16x16x32_bf16 v[118:121], v[122:125], v[40:43], v[118:121]
	ds_read_b128 v[122:125], v0 offset:64
	v_cmp_lt_i32_e32 vcc, s68, v105
	s_or_b64 s[16:17], s[0:1], vcc
	s_waitcnt lgkmcnt(1)
	v_mfma_f32_16x16x32_bf16 v[44:47], v[126:129], v[44:47], 0
	v_cmp_ge_u32_e32 vcc, v103, v101
	s_and_b64 vcc, s[16:17], vcc
	v_or_b32_e32 v0, 1, v105
	s_waitcnt lgkmcnt(0)
	v_mfma_f32_16x16x32_bf16 v[40:43], v[122:125], v[40:43], v[44:47]
	v_or_b32_e32 v1, 2, v105
	v_or_b32_e32 v2, 3, v105
	s_mov_b32 s15, 0xff800000
	v_cndmask_b32_e32 v45, v96, v74, vcc
	v_cmp_lt_i32_e32 vcc, s69, v105
	s_or_b64 s[16:17], s[0:1], vcc
	v_cmp_ge_i32_e32 vcc, v0, v90
	s_and_b64 vcc, s[16:17], vcc
	v_add_u32_e32 v44, 0x80, v90
	v_cndmask_b32_e32 v0, v96, v75, vcc
	v_cmp_lt_i32_e32 vcc, s68, v1
	s_or_b64 s[16:17], s[0:1], vcc
	v_cmp_ge_i32_e32 vcc, v1, v90
	s_and_b64 vcc, vcc, s[16:17]
	v_max3_f32 v46, v45, s15, v0
	v_cndmask_b32_e32 v1, v96, v76, vcc
	v_cmp_lt_i32_e32 vcc, s68, v2
	s_or_b64 s[16:17], s[0:1], vcc
	v_cmp_ge_i32_e32 vcc, v2, v90
	s_and_b64 vcc, vcc, s[16:17]
	v_and_b32_e32 v104, 24, v104
	v_cndmask_b32_e32 v47, v96, v77, vcc
	v_max3_f32 v2, v46, v1, v47
	v_or_b32_e32 v46, s71, v103
	v_cmp_lt_i32_e32 vcc, s68, v46
	s_or_b64 vcc, s[0:1], vcc
	v_or_b32_e32 v76, 2, v46
	v_cndmask_b32_e32 v74, v96, v78, vcc
	v_cmp_lt_i32_e32 vcc, s69, v46
	s_or_b64 vcc, s[0:1], vcc
	v_or_b32_e32 v46, 3, v46
	v_cndmask_b32_e32 v75, v96, v79, vcc
	v_cmp_lt_i32_e32 vcc, s68, v76
	s_or_b64 vcc, s[0:1], vcc
	v_or_b32_e32 v77, s74, v103
	v_cndmask_b32_e32 v76, v96, v80, vcc
	v_cmp_lt_i32_e32 vcc, s68, v46
	s_or_b64 vcc, s[0:1], vcc
	v_or_b32_e32 v80, 2, v77
	v_cndmask_b32_e32 v46, v96, v81, vcc
	v_cmp_lt_i32_e32 vcc, s68, v77
	s_or_b64 vcc, s[0:1], vcc
	v_or_b32_e32 v81, s37, v103
	v_cndmask_b32_e32 v78, v96, v82, vcc
	v_cmp_lt_i32_e32 vcc, s69, v77
	s_or_b64 vcc, s[0:1], vcc
	v_or_b32_e32 v77, 3, v77
	v_cndmask_b32_e32 v79, v96, v83, vcc
	v_cmp_lt_i32_e32 vcc, s68, v80
	s_or_b64 vcc, s[0:1], vcc
	v_or_b32_e32 v82, 2, v81
	v_cndmask_b32_e32 v80, v96, v84, vcc
	v_cmp_lt_i32_e32 vcc, s68, v77
	s_or_b64 vcc, s[0:1], vcc
	v_max3_f32 v2, v2, v74, v75
	v_cndmask_b32_e32 v77, v96, v85, vcc
	v_cmp_lt_i32_e32 vcc, s68, v81
	s_or_b64 vcc, s[0:1], vcc
	v_max3_f32 v2, v2, v76, v46
	v_cndmask_b32_e32 v90, v96, v86, vcc
	v_cmp_lt_i32_e32 vcc, s69, v81
	s_or_b64 vcc, s[0:1], vcc
	v_or_b32_e32 v81, 3, v81
	v_cndmask_b32_e32 v91, v96, v87, vcc
	v_cmp_lt_i32_e32 vcc, s68, v82
	s_or_b64 vcc, s[0:1], vcc
	v_max3_f32 v2, v2, v78, v79
	v_cndmask_b32_e32 v122, v96, v88, vcc
	v_cmp_lt_i32_e32 vcc, s68, v81
	s_or_b64 vcc, s[0:1], vcc
	v_or_b32_e32 v81, s42, v103
	v_cndmask_b32_e32 v123, v96, v89, vcc
	v_cmp_lt_i32_e32 vcc, s68, v81
	s_or_b64 vcc, s[0:1], vcc
	v_or_b32_e32 v82, 2, v81
	v_cndmask_b32_e32 v124, v96, v106, vcc
	v_cmp_lt_i32_e32 vcc, s69, v81
	s_or_b64 vcc, s[0:1], vcc
	v_or_b32_e32 v81, 3, v81
	v_cndmask_b32_e32 v125, v96, v107, vcc
	v_cmp_lt_i32_e32 vcc, s68, v82
	s_or_b64 vcc, s[0:1], vcc
	v_max3_f32 v2, v2, v80, v77
	v_cndmask_b32_e32 v126, v96, v108, vcc
	v_cmp_lt_i32_e32 vcc, s68, v81
	s_or_b64 vcc, s[0:1], vcc
	v_or_b32_e32 v81, s46, v103
	v_cndmask_b32_e32 v127, v96, v109, vcc
	v_cmp_lt_i32_e32 vcc, s68, v81
	s_or_b64 vcc, s[0:1], vcc
	v_or_b32_e32 v82, 2, v81
	v_cndmask_b32_e32 v128, v96, v110, vcc
	v_cmp_lt_i32_e32 vcc, s69, v81
	s_or_b64 vcc, s[0:1], vcc
	v_or_b32_e32 v81, 3, v81
	v_cndmask_b32_e32 v129, v96, v111, vcc
	v_cmp_lt_i32_e32 vcc, s68, v82
	s_or_b64 vcc, s[0:1], vcc
	v_max3_f32 v2, v2, v90, v91
	v_cndmask_b32_e32 v130, v96, v112, vcc
	v_cmp_lt_i32_e32 vcc, s68, v81
	s_or_b64 vcc, s[0:1], vcc
	v_or_b32_e32 v81, s48, v103
	v_cndmask_b32_e32 v131, v96, v113, vcc
	v_cmp_lt_i32_e32 vcc, s68, v81
	s_or_b64 vcc, s[0:1], vcc
	v_or_b32_e32 v82, 2, v81
	v_cndmask_b32_e32 v132, v96, v114, vcc
	v_cmp_lt_i32_e32 vcc, s69, v81
	s_or_b64 vcc, s[0:1], vcc
	v_or_b32_e32 v81, 3, v81
	v_cndmask_b32_e32 v115, v96, v115, vcc
	v_cmp_lt_i32_e32 vcc, s68, v82
	s_or_b64 vcc, s[0:1], vcc
	v_max3_f32 v2, v2, v122, v123
	v_cndmask_b32_e32 v133, v96, v116, vcc
	v_cmp_lt_i32_e32 vcc, s68, v81
	v_max3_f32 v2, v2, v124, v125
	s_or_b64 vcc, s[0:1], vcc
	v_or_b32_e32 v81, s62, v103
	v_max3_f32 v2, v2, v126, v127
	v_cndmask_b32_e32 v134, v96, v117, vcc
	v_cmp_lt_i32_e32 vcc, s68, v81
	v_max3_f32 v2, v2, v128, v129
	s_or_b64 vcc, s[0:1], vcc
	v_max3_f32 v2, v2, v130, v131
	v_cndmask_b32_e32 v112, v96, v118, vcc
	v_cmp_lt_i32_e32 vcc, s69, v81
	v_max3_f32 v2, v2, v132, v115
	s_or_b64 vcc, s[0:1], vcc
	v_max3_f32 v2, v2, v133, v134
	v_cndmask_b32_e32 v113, v96, v119, vcc
	v_max3_f32 v82, v2, v112, v113
	v_or_b32_e32 v2, 2, v81
	v_cmp_lt_i32_e32 vcc, s68, v2
	s_or_b64 vcc, s[0:1], vcc
	v_or_b32_e32 v2, 3, v81
	v_cndmask_b32_e32 v114, v96, v120, vcc
	v_cmp_lt_i32_e32 vcc, s68, v2
	s_or_b64 vcc, s[0:1], vcc
	v_lshrrev_b32_e32 v116, 2, v101
	v_cndmask_b32_e32 v2, v96, v121, vcc
	v_max3_f32 v81, v82, v114, v2
	v_or_b32_e32 v82, s67, v103
	v_cmp_lt_i32_e32 vcc, s68, v82
	s_or_b64 s[16:17], s[0:1], vcc
	v_cmp_le_i32_e32 vcc, v82, v44
	s_and_b64 vcc, s[16:17], vcc
	v_or_b32_e32 v116, v103, v116
	v_cndmask_b32_e32 v108, v96, v40, vcc
	v_cmp_lt_i32_e32 vcc, s69, v82
	s_or_b64 s[16:17], s[0:1], vcc
	v_cmp_lt_i32_e32 vcc, v82, v44
	s_and_b64 vcc, s[16:17], vcc
	v_mul_u32_u24_e32 v116, 0x90, v116
	v_cndmask_b32_e32 v109, v96, v41, vcc
	v_or_b32_e32 v41, 2, v82
	v_cmp_lt_i32_e32 vcc, s68, v41
	s_or_b64 s[16:17], s[0:1], vcc
	v_cmp_le_i32_e32 vcc, v41, v44
	s_and_b64 vcc, s[16:17], vcc
	v_or_b32_e32 v41, 3, v82
	v_cndmask_b32_e32 v110, v96, v42, vcc
	v_cmp_lt_i32_e32 vcc, s68, v41
	s_or_b64 s[0:1], s[0:1], vcc
	v_cmp_le_i32_e32 vcc, v41, v44
	v_and_b32_e32 v42, 64, v95
	s_and_b64 vcc, s[0:1], vcc
	v_xor_b32_e32 v41, 16, v95
	v_add_u32_e32 v42, 64, v42
	v_cndmask_b32_e32 v111, v96, v43, vcc
	v_cmp_lt_i32_e32 vcc, v41, v42
	v_max3_f32 v40, v81, v108, v109
	v_max3_f32 v40, v40, v110, v111
	v_cndmask_b32_e32 v41, v95, v41, vcc
	v_lshlrev_b32_e32 v105, 2, v41
	ds_bpermute_b32 v41, v105, v40
	s_or_b32 s0, s14, s50
	v_add3_u32 v104, 0, v116, v104
	s_mulk_i32 s13, 0x90
	s_mulk_i32 s0, 0x90
	s_waitcnt lgkmcnt(0)
	v_max_f32_e32 v41, v41, v41
	v_max_f32_e32 v40, v40, v41
	v_xor_b32_e32 v41, 32, v95
	v_cmp_lt_i32_e32 vcc, v41, v42
	s_mulk_i32 s11, 0x90
	s_mulk_i32 s9, 0x90
	v_cndmask_b32_e32 v41, v95, v41, vcc
	v_lshlrev_b32_e32 v106, 2, v41
	ds_bpermute_b32 v41, v106, v40
	s_mulk_i32 s7, 0x90
	s_mulk_i32 s6, 0x90
	s_waitcnt lgkmcnt(0)
	v_max_f32_e32 v41, v41, v41
	v_max_f32_e32 v40, v40, v41
	v_mul_f32_e32 v40, 0x3e38aa3b, v40
	v_max_f32_e32 v41, v53, v53
	v_max_f32_e32 v107, v40, v41
	v_fma_f32 v42, v74, s70, -v107
	v_fma_f32 v1, v1, s70, -v107
	v_exp_f32_e32 v82, v42
	v_fma_f32 v42, v75, s70, -v107
	v_exp_f32_e32 v88, v1
	v_fma_f32 v1, v47, s70, -v107
	v_exp_f32_e32 v83, v42
	v_fma_f32 v42, v76, s70, -v107
	v_exp_f32_e32 v89, v1
	v_exp_f32_e32 v84, v42
	v_fma_f32 v42, v46, s70, -v107
	v_fma_f32 v43, v80, s70, -v107
	v_exp_f32_e32 v85, v42
	v_exp_f32_e32 v80, v43
	v_fma_f32 v43, v77, s70, -v107
	v_exp_f32_e32 v81, v43
	v_fma_f32 v0, v0, s70, -v107
	v_exp_f32_e32 v87, v0
	v_pk_add_f32 v[0:1], v[88:89], 0 op_sel_hi:[1,0]
	v_fma_f32 v42, v78, s70, -v107
	v_exp_f32_e32 v74, v42
	v_fma_f32 v42, v79, s70, -v107
	v_pk_add_f32 v[0:1], v[84:85], v[0:1]
	v_exp_f32_e32 v75, v42
	v_pk_add_f32 v[42:43], v[80:81], v[0:1]
	v_fma_f32 v0, v90, s70, -v107
	v_exp_f32_e32 v76, v0
	v_fma_f32 v0, v91, s70, -v107
	v_exp_f32_e32 v77, v0
	v_fma_f32 v0, v122, s70, -v107
	v_exp_f32_e32 v78, v0
	v_fma_f32 v0, v123, s70, -v107
	v_fma_f32 v40, v45, s70, -v107
	v_exp_f32_e32 v79, v0
	v_fma_f32 v44, v126, s70, -v107
	v_fma_f32 v45, v127, s70, -v107
	v_exp_f32_e32 v44, v44
	v_exp_f32_e32 v45, v45
	v_exp_f32_e32 v86, v40
	v_pk_add_f32 v[42:43], v[78:79], v[42:43]
	v_fma_f32 v0, v124, s70, -v107
	v_fma_f32 v1, v125, s70, -v107
	v_pk_add_f32 v[46:47], v[44:45], v[42:43]
	v_fma_f32 v42, v130, s70, -v107
	v_add_u32_e32 v126, s13, v104
	v_add_u32_e32 v130, s0, v104
	v_pk_add_f32 v[40:41], v[86:87], 0 op_sel_hi:[1,0]
	v_exp_f32_e32 v0, v0
	v_exp_f32_e32 v1, v1
	ds_read_b64_tr_b16 v[116:117], v126 offset:36864
	ds_read_b64_tr_b16 v[118:119], v130 offset:36864
	v_pk_add_f32 v[40:41], v[82:83], v[40:41]
	v_fma_f32 v43, v131, s70, -v107
	v_pk_add_f32 v[40:41], v[74:75], v[40:41]
	s_or_b32 s0, s12, s51
	v_pk_add_f32 v[40:41], v[76:77], v[40:41]
	s_mulk_i32 s0, 0x90
	v_pk_add_f32 v[90:91], v[0:1], v[40:41]
	v_fma_f32 v40, v128, s70, -v107
	v_fma_f32 v41, v129, s70, -v107
	ds_read_b64_tr_b16 v[122:123], v130 offset:36896
	ds_read_b64_tr_b16 v[120:121], v126 offset:36896
	ds_read_b64_tr_b16 v[124:125], v126 offset:36928
	ds_read_b64_tr_b16 v[128:129], v126 offset:36960
	ds_read_b64_tr_b16 v[126:127], v130 offset:36928
	ds_read_b64_tr_b16 v[130:131], v130 offset:36960
	v_cvt_pk_bf16_f32 v86, v86, v87
	v_cvt_pk_bf16_f32 v87, v88, v89
	v_cvt_pk_bf16_f32 v88, v82, v83
	v_cvt_pk_bf16_f32 v89, v84, v85
	v_fma_f32 v83, v115, s70, -v107
	v_add_u32_e32 v115, s11, v104
	v_add_u32_e32 v138, s0, v104
	s_waitcnt lgkmcnt(6)
	v_mfma_f32_16x16x32_bf16 v[116:119], v[116:119], v[86:89], 0
	v_fma_f32 v82, v132, s70, -v107
	v_fma_f32 v84, v133, s70, -v107
	v_fma_f32 v85, v134, s70, -v107
	s_waitcnt lgkmcnt(4)
	v_mfma_f32_16x16x32_bf16 v[120:123], v[120:123], v[86:89], 0
	v_cvt_pk_bf16_f32 v74, v74, v75
	v_cvt_pk_bf16_f32 v75, v80, v81
	v_cvt_pk_bf16_f32 v76, v76, v77
	s_waitcnt lgkmcnt(1)
	v_mfma_f32_16x16x32_bf16 v[124:127], v[124:127], v[86:89], 0
	v_cvt_pk_bf16_f32 v77, v78, v79
	v_fma_f32 v112, v112, s70, -v107
	s_or_b32 s0, s10, s33
	s_waitcnt lgkmcnt(0)
	v_mfma_f32_16x16x32_bf16 v[86:89], v[128:131], v[86:89], 0
	ds_read_b64_tr_b16 v[128:129], v115 offset:36864
	ds_read_b64_tr_b16 v[130:131], v138 offset:36864
	ds_read_b64_tr_b16 v[80:81], v138 offset:36896
	ds_read_b64_tr_b16 v[78:79], v115 offset:36896
	ds_read_b64_tr_b16 v[132:133], v115 offset:36928
	ds_read_b64_tr_b16 v[136:137], v115 offset:36960
	ds_read_b64_tr_b16 v[134:135], v138 offset:36928
	ds_read_b64_tr_b16 v[138:139], v138 offset:36960
	v_exp_f32_e32 v140, v112
	v_fma_f32 v112, v113, s70, -v107
	s_mulk_i32 s0, 0x90
	s_waitcnt lgkmcnt(6)
	v_mfma_f32_16x16x32_bf16 v[116:119], v[128:131], v[74:77], v[116:119]
	v_exp_f32_e32 v141, v112
	v_fma_f32 v112, v114, s70, -v107
	v_exp_f32_e32 v40, v40
	s_waitcnt lgkmcnt(4)
	v_mfma_f32_16x16x32_bf16 v[78:81], v[78:81], v[74:77], v[120:123]
	v_exp_f32_e32 v41, v41
	v_exp_f32_e32 v42, v42
	v_exp_f32_e32 v43, v43
	s_waitcnt lgkmcnt(1)
	v_mfma_f32_16x16x32_bf16 v[120:123], v[132:135], v[74:77], v[124:127]
	v_exp_f32_e32 v132, v112
	v_exp_f32_e32 v82, v82
	v_exp_f32_e32 v83, v83
	s_waitcnt lgkmcnt(0)
	v_mfma_f32_16x16x32_bf16 v[74:77], v[136:139], v[74:77], v[86:89]
	v_add_f32_e64 v90, v40, v90
	v_add_f32_e64 v91, v41, v91
	v_pk_add_f32 v[46:47], v[42:43], v[46:47]
	v_exp_f32_e32 v84, v84
	v_cvt_pk_bf16_f32 v86, v0, v1
	v_add_u32_e32 v0, s9, v104
	v_add_u32_e32 v1, s0, v104
	ds_read_b64_tr_b16 v[112:113], v0 offset:36864
	ds_read_b64_tr_b16 v[114:115], v1 offset:36864
	v_cvt_pk_bf16_f32 v88, v40, v41
	v_cvt_pk_bf16_f32 v89, v42, v43
	ds_read_b64_tr_b16 v[42:43], v1 offset:36896
	ds_read_b64_tr_b16 v[40:41], v0 offset:36896
	ds_read_b64_tr_b16 v[124:125], v0 offset:36928
	ds_read_b64_tr_b16 v[128:129], v0 offset:36960
	ds_read_b64_tr_b16 v[126:127], v1 offset:36928
	ds_read_b64_tr_b16 v[130:131], v1 offset:36960
	s_or_b32 s0, s8, s35
	v_exp_f32_e32 v85, v85
	v_pk_add_f32 v[90:91], v[82:83], v[90:91]
	v_cvt_pk_bf16_f32 v87, v44, v45
	v_fma_f32 v0, v2, s70, -v107
	v_fma_f32 v2, v108, s70, -v107
	v_fma_f32 v44, v110, s70, -v107
	s_mulk_i32 s0, 0x90
	v_exp_f32_e32 v133, v0
	v_pk_add_f32 v[0:1], v[140:141], v[90:91]
	s_waitcnt lgkmcnt(4)
	v_mfma_f32_16x16x32_bf16 v[40:43], v[40:43], v[86:89], v[78:81]
	v_exp_f32_e32 v90, v2
	v_fma_f32 v2, v109, s70, -v107
	v_add_u32_e32 v45, s7, v104
	s_waitcnt lgkmcnt(1)
	v_mfma_f32_16x16x32_bf16 v[78:81], v[124:127], v[86:89], v[120:123]
	v_exp_f32_e32 v124, v44
	v_fma_f32 v44, v111, s70, -v107
	v_add_u32_e32 v91, s0, v104
	v_mfma_f32_16x16x32_bf16 v[112:115], v[112:115], v[86:89], v[116:119]
	v_exp_f32_e32 v125, v44
	v_pk_add_f32 v[46:47], v[84:85], v[46:47]
	s_and_b64 s[0:1], s[52:53], exec
	s_waitcnt lgkmcnt(0)
	v_mfma_f32_16x16x32_bf16 v[74:77], v[128:131], v[86:89], v[74:77]
	ds_read_b64_tr_b16 v[86:87], v45 offset:36864
	ds_read_b64_tr_b16 v[88:89], v91 offset:36864
	ds_read_b64_tr_b16 v[110:111], v91 offset:36896
	ds_read_b64_tr_b16 v[108:109], v45 offset:36896
	ds_read_b64_tr_b16 v[116:117], v45 offset:36928
	ds_read_b64_tr_b16 v[120:121], v45 offset:36960
	ds_read_b64_tr_b16 v[118:119], v91 offset:36928
	ds_read_b64_tr_b16 v[122:123], v91 offset:36960
	v_exp_f32_e32 v91, v2
	v_cvt_pk_bf16_f32 v82, v82, v83
	v_cvt_pk_bf16_f32 v83, v84, v85
	v_cvt_pk_bf16_f32 v84, v140, v141
	v_cvt_pk_bf16_f32 v85, v132, v133
	v_pk_add_f32 v[44:45], v[132:133], v[46:47]
	s_cselect_b32 s0, s96, s41
	s_waitcnt lgkmcnt(4)
	v_mfma_f32_16x16x32_bf16 v[40:43], v[108:111], v[82:85], v[40:43]
	v_add_f32_e64 v108, v124, v44
	v_add_f32_e64 v109, v125, v45
	v_pk_add_f32 v[0:1], v[90:91], v[0:1]
	s_lshl_b32 s0, s0, 7
	v_pk_mov_b32 v[110:111], v[0:1], v[108:109] op_sel:[1,0]
	v_mov_b32_e32 v1, v109
	s_or_b32 s0, s0, s75
	v_pk_add_f32 v[0:1], v[110:111], v[0:1]
	s_mulk_i32 s0, 0x90
	s_waitcnt lgkmcnt(1)
	v_mfma_f32_16x16x32_bf16 v[44:47], v[116:119], v[82:85], v[78:81]
	v_add_f32_e32 v116, v0, v1
	v_cvt_pk_bf16_f32 v0, v90, v91
	v_add_u32_e32 v90, s6, v104
	v_add_u32_e32 v91, s0, v104
	ds_read_b64_tr_b16 v[78:79], v90 offset:36864
	ds_read_b64_tr_b16 v[80:81], v91 offset:36864
	v_mfma_f32_16x16x32_bf16 v[86:89], v[86:89], v[82:85], v[112:115]
	v_cvt_pk_bf16_f32 v1, v124, v125
	v_mov_b32_e32 v2, v3
	s_waitcnt vmcnt(0)
	v_permlane16_swap_b32_e32 v238, v240
	v_permlane16_swap_b32_e32 v239, v241
	v_permlane16_swap_b32_e32 v242, v244
	v_permlane16_swap_b32_e32 v243, v245
	v_permlane16_swap_b32_e32 v246, v248
	v_permlane16_swap_b32_e32 v247, v249
	v_permlane16_swap_b32_e32 v250, v252
	v_permlane16_swap_b32_e32 v251, v253
	v_permlane16_swap_b32_e32 v154, v156
	v_permlane16_swap_b32_e32 v155, v157
	v_permlane16_swap_b32_e32 v216, v218
	v_permlane16_swap_b32_e32 v217, v219
	v_mov_b64_e32 v[68:69], v[238:239]
	v_mov_b64_e32 v[62:63], v[240:241]
	v_mov_b64_e32 v[56:57], v[242:243]
	v_mov_b64_e32 v[48:49], v[244:245]
	v_mov_b64_e32 v[70:71], v[246:247]
	v_mov_b64_e32 v[64:65], v[248:249]
	v_mov_b64_e32 v[58:59], v[250:251]
	v_mov_b64_e32 v[50:51], v[252:253]
	v_mov_b64_e32 v[72:73], v[154:155]
	v_mov_b64_e32 v[66:67], v[156:157]
	v_mov_b64_e32 v[60:61], v[216:217]
	v_mov_b64_e32 v[54:55], v[218:219]
	v_and_b32_e32 v104, 0xffff0000, v70
	s_waitcnt lgkmcnt(2)
	v_mfma_f32_16x16x32_bf16 v[74:77], v[120:123], v[82:85], v[74:77]
	ds_read_b64_tr_b16 v[84:85], v91 offset:36896
	ds_read_b64_tr_b16 v[82:83], v90 offset:36896
	ds_read_b64_tr_b16 v[108:109], v90 offset:36928
	ds_read_b64_tr_b16 v[112:113], v90 offset:36960
	ds_read_b64_tr_b16 v[110:111], v91 offset:36928
	ds_read_b64_tr_b16 v[114:115], v91 offset:36960
	v_lshlrev_b32_e32 v90, 16, v70
	v_mul_f32_e32 v90, 0xbfb8aa3b, v90
	s_waitcnt lgkmcnt(6)
	v_mfma_f32_16x16x32_bf16 v[78:81], v[78:81], v[0:3], v[86:89]
	v_exp_f32_e32 v90, v90
	s_add_i32 s40, s40, 1
	s_nop 0
	ds_bpermute_b32 v86, v105, v116
	s_waitcnt lgkmcnt(5)
	v_mfma_f32_16x16x32_bf16 v[82:85], v[82:85], v[0:3], v[40:43]
	v_lshlrev_b32_e32 v88, 16, v73
	v_and_b32_e32 v89, 0xffff0000, v73
	v_lshlrev_b32_e32 v105, 16, v71
	s_waitcnt lgkmcnt(0)
	v_add_f32_e32 v40, v116, v86
	ds_bpermute_b32 v41, v106, v40
	v_sub_f32_e32 v42, v53, v107
	v_exp_f32_e32 v42, v42
	v_mfma_f32_16x16x32_bf16 v[44:47], v[108:111], v[0:3], v[44:47]
	v_and_b32_e32 v106, 0xffff0000, v69
	s_waitcnt lgkmcnt(0)
	v_add_f32_e32 v40, v40, v41
	v_add_f32_e32 v86, v42, v40
	v_mfma_f32_16x16x32_bf16 v[40:43], v[112:115], v[0:3], v[74:77]
	v_lshl_add_u32 v1, v103, 2, v102
	v_lshlrev_b32_e32 v2, 16, v68
	v_lshlrev_b32_e32 v102, 16, v69
	v_add_u32_e32 v74, s38, v101
	s_mov_b32 s100, 0x9f57000
	v_lshl_add_u64 v[22:23], v[20:21], 0, s[100:101]
	global_load_dwordx4 v[28:31], v[22:23], off offset:3072
	v_and_b32_e32 v101, 0xffff0000, v68
	v_lshlrev_b32_e32 v68, 16, v72
	v_and_b32_e32 v69, 0xffff0000, v72
	v_pk_mul_f32 v[72:73], v[68:69], v[68:69]
	v_mul_f32_e32 v2, 0xbfb8aa3b, v2
	v_fmamk_f32 v72, v72, 0xbdd2d3e7, v93
	v_mul_f32_e32 v72, v72, v68
	v_exp_f32_e32 v2, v2
	v_exp_f32_e32 v91, v72
	v_mul_f32_e32 v72, 0xbfb8aa3b, v101
	v_fmamk_f32 v73, v73, 0xbdd2d3e7, v93
	v_and_b32_e32 v107, 0xffff0000, v71
	v_pk_mul_f32 v[70:71], v[88:89], v[88:89]
	v_exp_f32_e32 v101, v72
	v_mul_f32_e32 v72, 0xbfb8aa3b, v104
	v_mul_f32_e32 v73, v73, v69
	v_exp_f32_e32 v72, v72
	v_exp_f32_e32 v73, v73
	v_fmamk_f32 v70, v70, 0xbdd2d3e7, v93
	v_mul_f32_e32 v102, 0xbfb8aa3b, v102
	v_mul_f32_e32 v104, 0xbfb8aa3b, v105
	v_mul_f32_e32 v70, v70, v88
	v_exp_f32_e32 v102, v102
	v_exp_f32_e32 v104, v104
	v_exp_f32_e32 v105, v70
	v_mul_f32_e32 v70, 0xbfb8aa3b, v106
	v_fmamk_f32 v71, v71, 0xbdd2d3e7, v93
	v_add_f32_e32 v2, 1.0, v2
	v_pk_add_f32 v[90:91], v[90:91], 1.0 op_sel_hi:[1,0]
	v_exp_f32_e32 v109, v70
	v_mul_f32_e32 v70, 0xbfb8aa3b, v107
	v_mul_f32_e32 v71, v71, v89
	v_rcp_f32_e32 v106, v2
	v_mul_f32_e32 v2, v90, v91
	v_exp_f32_e32 v70, v70
	v_exp_f32_e32 v71, v71
	v_rcp_f32_e32 v90, v2
	v_add_f32_e32 v2, 1.0, v101
	v_pk_add_f32 v[72:73], v[72:73], 1.0 op_sel_hi:[1,0]
	v_rcp_f32_e32 v107, v2
	v_mul_f32_e32 v2, v72, v73
	v_ashrrev_i32_e32 v75, 31, v74
	v_rcp_f32_e32 v91, v2
	v_add_f32_e32 v2, 1.0, v102
	v_pk_add_f32 v[72:73], v[104:105], 1.0 op_sel_hi:[1,0]
	v_lshlrev_b64 v[74:75], 11, v[74:75]
	v_rcp_f32_e32 v108, v2
	v_mul_f32_e32 v2, v72, v73
	v_rcp_f32_e32 v0, v86
	v_lshl_add_u64 v[86:87], s[44:45], 0, v[74:75]
	ds_read_b128 v[74:77], v1
	v_rcp_f32_e32 v104, v2
	v_add_f32_e32 v2, 1.0, v109
	v_pk_add_f32 v[70:71], v[70:71], 1.0 op_sel_hi:[1,0]
	v_rcp_f32_e32 v109, v2
	v_mul_f32_e32 v2, v70, v71
	v_rcp_f32_e32 v105, v2
	ds_read_b128 v[70:73], v1 offset:64
	s_waitcnt lgkmcnt(1)
	v_pk_mul_f32 v[76:77], v[76:77], v[88:89]
	v_pk_mul_f32 v[68:69], v[74:75], v[68:69]
	v_pk_mul_f32 v[80:81], v[0:1], v[80:81] op_sel_hi:[0,1]
	v_pk_mul_f32 v[78:79], v[0:1], v[78:79] op_sel_hi:[0,1]
	v_pk_mul_f32 v[68:69], v[90:91], v[68:69]
	v_pk_mul_f32 v[74:75], v[104:105], v[76:77]
	v_pk_fma_f32 v[68:69], v[106:107], v[78:79], v[68:69]
	v_pk_fma_f32 v[74:75], v[108:109], v[80:81], v[74:75]
	v_lshlrev_b32_e32 v2, 1, v103
	v_cvt_pk_bf16_f32 v76, v68, v69
	v_cvt_pk_bf16_f32 v77, v74, v75
	v_lshl_add_u64 v[68:69], v[86:87], 0, v[2:3]
	global_store_dwordx2 v[68:69], v[76:77], off
	v_pk_mul_f32 v[74:75], v[0:1], v[84:85] op_sel_hi:[0,1]
	v_pk_mul_f32 v[76:77], v[0:1], v[82:83] op_sel_hi:[0,1]
	v_lshlrev_b32_e32 v2, 16, v62
	v_and_b32_e32 v82, 0xffff0000, v62
	v_lshlrev_b32_e32 v83, 16, v63
	v_and_b32_e32 v84, 0xffff0000, v63
	v_lshlrev_b32_e32 v62, 16, v66
	v_and_b32_e32 v63, 0xffff0000, v66
	v_pk_mul_f32 v[78:79], v[62:63], v[62:63]
	v_lshlrev_b32_e32 v80, 16, v64
	v_fmamk_f32 v78, v78, 0xbdd2d3e7, v93
	v_mul_f32_e32 v2, 0xbfb8aa3b, v2
	v_mul_f32_e32 v80, 0xbfb8aa3b, v80
	v_mul_f32_e32 v78, v78, v62
	v_and_b32_e32 v85, 0xffff0000, v64
	v_lshlrev_b32_e32 v86, 16, v65
	v_and_b32_e32 v87, 0xffff0000, v65
	s_mov_b32 s100, 0x9f5a000
	v_lshl_add_u64 v[24:25], v[20:21], 0, s[100:101]
	global_load_dwordx4 v[24:27], v[24:25], off offset:2048
	v_lshlrev_b32_e32 v64, 16, v67
	v_and_b32_e32 v65, 0xffff0000, v67
	v_exp_f32_e32 v2, v2
	v_exp_f32_e32 v80, v80
	v_exp_f32_e32 v81, v78
	v_mul_f32_e32 v78, 0xbfb8aa3b, v82
	v_fmamk_f32 v79, v79, 0xbdd2d3e7, v93
	v_pk_mul_f32 v[66:67], v[64:65], v[64:65]
	v_exp_f32_e32 v88, v78
	v_mul_f32_e32 v78, 0xbfb8aa3b, v85
	v_mul_f32_e32 v79, v79, v63
	v_exp_f32_e32 v78, v78
	v_exp_f32_e32 v79, v79
	v_mul_f32_e32 v82, 0xbfb8aa3b, v83
	v_fmamk_f32 v66, v66, 0xbdd2d3e7, v93
	v_exp_f32_e32 v89, v82
	v_mul_f32_e32 v82, 0xbfb8aa3b, v86
	v_mul_f32_e32 v66, v66, v64
	v_exp_f32_e32 v82, v82
	v_exp_f32_e32 v83, v66
	v_mul_f32_e32 v66, 0xbfb8aa3b, v84
	v_fmamk_f32 v67, v67, 0xbdd2d3e7, v93
	v_add_f32_e32 v2, 1.0, v2
	v_pk_add_f32 v[80:81], v[80:81], 1.0 op_sel_hi:[1,0]
	v_exp_f32_e32 v86, v66
	v_mul_f32_e32 v66, 0xbfb8aa3b, v87
	v_mul_f32_e32 v67, v67, v65
	v_rcp_f32_e32 v84, v2
	v_mul_f32_e32 v2, v80, v81
	v_exp_f32_e32 v66, v66
	v_exp_f32_e32 v67, v67
	v_rcp_f32_e32 v80, v2
	v_add_f32_e32 v2, 1.0, v88
	v_pk_add_f32 v[78:79], v[78:79], 1.0 op_sel_hi:[1,0]
	v_rcp_f32_e32 v85, v2
	v_mul_f32_e32 v2, v78, v79
	v_rcp_f32_e32 v81, v2
	v_add_f32_e32 v2, 1.0, v89
	v_pk_add_f32 v[82:83], v[82:83], 1.0 op_sel_hi:[1,0]
	v_rcp_f32_e32 v78, v2
	v_mul_f32_e32 v2, v82, v83
	v_rcp_f32_e32 v82, v2
	v_add_f32_e32 v2, 1.0, v86
	v_pk_add_f32 v[66:67], v[66:67], 1.0 op_sel_hi:[1,0]
	v_rcp_f32_e32 v79, v2
	v_mul_f32_e32 v2, v66, v67
	v_rcp_f32_e32 v83, v2
	s_waitcnt lgkmcnt(0)
	v_pk_mul_f32 v[64:65], v[72:73], v[64:65]
	v_lshlrev_b32_e32 v2, 16, v56
	v_and_b32_e32 v72, 0xffff0000, v56
	v_pk_mul_f32 v[64:65], v[82:83], v[64:65]
	v_lshlrev_b32_e32 v73, 16, v57
	v_pk_fma_f32 v[64:65], v[78:79], v[74:75], v[64:65]
	v_and_b32_e32 v74, 0xffff0000, v57
	v_lshlrev_b32_e32 v56, 16, v60
	v_and_b32_e32 v57, 0xffff0000, v60
	v_pk_mul_f32 v[66:67], v[0:1], v[46:47] op_sel_hi:[0,1]
	v_pk_mul_f32 v[46:47], v[56:57], v[56:57]
	v_pk_mul_f32 v[62:63], v[70:71], v[62:63]
	v_lshlrev_b32_e32 v75, 16, v58
	v_fmamk_f32 v46, v46, 0xbdd2d3e7, v93
	v_pk_mul_f32 v[62:63], v[80:81], v[62:63]
	v_mul_f32_e32 v2, 0xbfb8aa3b, v2
	v_mul_f32_e32 v60, 0xbfb8aa3b, v75
	v_mul_f32_e32 v46, v46, v56
	v_pk_fma_f32 v[62:63], v[84:85], v[76:77], v[62:63]
	v_and_b32_e32 v76, 0xffff0000, v58
	v_lshlrev_b32_e32 v77, 16, v59
	v_and_b32_e32 v78, 0xffff0000, v59
	v_lshlrev_b32_e32 v58, 16, v61
	v_and_b32_e32 v59, 0xffff0000, v61
	v_exp_f32_e32 v2, v2
	v_exp_f32_e32 v60, v60
	s_mov_b32 s100, 0x9f5d000
	v_lshl_add_u64 v[22:23], v[20:21], 0, s[100:101]
	global_load_dwordx4 v[36:39], v[22:23], off offset:1024
	v_exp_f32_e32 v61, v46
	v_mul_f32_e32 v46, 0xbfb8aa3b, v72
	v_fmamk_f32 v47, v47, 0xbdd2d3e7, v93
	v_pk_mul_f32 v[70:71], v[0:1], v[44:45] op_sel_hi:[0,1]
	v_pk_mul_f32 v[44:45], v[58:59], v[58:59]
	v_exp_f32_e32 v75, v46
	v_mul_f32_e32 v46, 0xbfb8aa3b, v76
	v_mul_f32_e32 v47, v47, v57
	v_exp_f32_e32 v46, v46
	v_exp_f32_e32 v47, v47
	v_mul_f32_e32 v72, 0xbfb8aa3b, v73
	v_fmamk_f32 v44, v44, 0xbdd2d3e7, v93
	v_exp_f32_e32 v76, v72
	v_mul_f32_e32 v72, 0xbfb8aa3b, v77
	v_mul_f32_e32 v44, v44, v58
	v_exp_f32_e32 v72, v72
	v_exp_f32_e32 v73, v44
	v_mul_f32_e32 v44, 0xbfb8aa3b, v74
	v_fmamk_f32 v45, v45, 0xbdd2d3e7, v93
	v_add_f32_e32 v2, 1.0, v2
	v_pk_add_f32 v[60:61], v[60:61], 1.0 op_sel_hi:[1,0]
	v_exp_f32_e32 v77, v44
	v_mul_f32_e32 v44, 0xbfb8aa3b, v78
	v_mul_f32_e32 v45, v45, v59
	v_rcp_f32_e32 v74, v2
	v_mul_f32_e32 v2, v60, v61
	v_exp_f32_e32 v44, v44
	v_exp_f32_e32 v45, v45
	v_rcp_f32_e32 v60, v2
	v_add_f32_e32 v2, 1.0, v75
	v_pk_add_f32 v[46:47], v[46:47], 1.0 op_sel_hi:[1,0]
	v_rcp_f32_e32 v75, v2
	v_mul_f32_e32 v2, v46, v47
	v_rcp_f32_e32 v61, v2
	v_add_f32_e32 v2, 1.0, v76
	v_pk_add_f32 v[46:47], v[72:73], 1.0 op_sel_hi:[1,0]
	v_cvt_pk_bf16_f32 v62, v62, v63
	v_cvt_pk_bf16_f32 v63, v64, v65
	v_rcp_f32_e32 v76, v2
	v_mul_f32_e32 v2, v46, v47
	global_store_dwordx2 v[68:69], v[62:63], off offset:32
	ds_read_b128 v[62:65], v1 offset:128
	v_rcp_f32_e32 v72, v2
	v_add_f32_e32 v2, 1.0, v77
	v_pk_add_f32 v[44:45], v[44:45], 1.0 op_sel_hi:[1,0]
	v_rcp_f32_e32 v77, v2
	v_mul_f32_e32 v2, v44, v45
	v_rcp_f32_e32 v73, v2
	ds_read_b128 v[44:47], v1 offset:192
	s_waitcnt lgkmcnt(1)
	v_pk_mul_f32 v[58:59], v[64:65], v[58:59]
	v_pk_mul_f32 v[56:57], v[62:63], v[56:57]
	v_pk_mul_f32 v[58:59], v[72:73], v[58:59]
	v_pk_mul_f32 v[56:57], v[60:61], v[56:57]
	v_pk_fma_f32 v[58:59], v[76:77], v[66:67], v[58:59]
	v_pk_fma_f32 v[56:57], v[74:75], v[70:71], v[56:57]
	v_pk_mul_f32 v[42:43], v[0:1], v[42:43] op_sel_hi:[0,1]
	v_pk_mul_f32 v[0:1], v[0:1], v[40:41] op_sel_hi:[0,1]
	v_lshlrev_b32_e32 v40, 16, v54
	s_mov_b32 s100, s66
	v_lshl_add_u64 v[32:33], v[20:21], 0, s[100:101]
	global_load_dwordx4 v[32:35], v[32:33], off
	v_and_b32_e32 v41, 0xffff0000, v54
	v_cvt_pk_bf16_f32 v56, v56, v57
	v_cvt_pk_bf16_f32 v57, v58, v59
	v_lshlrev_b32_e32 v2, 16, v48
	v_and_b32_e32 v58, 0xffff0000, v48
	v_lshlrev_b32_e32 v59, 16, v49
	v_and_b32_e32 v60, 0xffff0000, v49
	v_lshlrev_b32_e32 v48, 16, v55
	v_and_b32_e32 v49, 0xffff0000, v55
	v_pk_mul_f32 v[54:55], v[40:41], v[40:41]
	global_store_dwordx2 v[68:69], v[56:57], off offset:64
	v_lshlrev_b32_e32 v56, 16, v50
	v_fmamk_f32 v54, v54, 0xbdd2d3e7, v93
	v_mul_f32_e32 v2, 0xbfb8aa3b, v2
	v_mul_f32_e32 v56, 0xbfb8aa3b, v56
	v_mul_f32_e32 v54, v54, v40
	v_and_b32_e32 v61, 0xffff0000, v50
	v_exp_f32_e32 v2, v2
	v_exp_f32_e32 v56, v56
	v_exp_f32_e32 v57, v54
	v_mul_f32_e32 v54, 0xbfb8aa3b, v58
	v_fmamk_f32 v55, v55, 0xbdd2d3e7, v93
	v_lshlrev_b32_e32 v62, 16, v51
	v_and_b32_e32 v63, 0xffff0000, v51
	v_pk_mul_f32 v[50:51], v[48:49], v[48:49]
	v_exp_f32_e32 v64, v54
	v_mul_f32_e32 v54, 0xbfb8aa3b, v61
	v_mul_f32_e32 v55, v55, v41
	v_exp_f32_e32 v54, v54
	v_exp_f32_e32 v55, v55
	v_mul_f32_e32 v58, 0xbfb8aa3b, v59
	v_fmamk_f32 v50, v50, 0xbdd2d3e7, v93
	v_exp_f32_e32 v65, v58
	v_mul_f32_e32 v58, 0xbfb8aa3b, v62
	v_mul_f32_e32 v50, v50, v48
	v_exp_f32_e32 v58, v58
	v_exp_f32_e32 v59, v50
	v_mul_f32_e32 v50, 0xbfb8aa3b, v60
	v_fmamk_f32 v51, v51, 0xbdd2d3e7, v93
	v_add_f32_e32 v2, 1.0, v2
	v_pk_add_f32 v[56:57], v[56:57], 1.0 op_sel_hi:[1,0]
	v_exp_f32_e32 v62, v50
	v_mul_f32_e32 v50, 0xbfb8aa3b, v63
	v_mul_f32_e32 v51, v51, v49
	v_rcp_f32_e32 v60, v2
	s_mov_b32 s100, 0x9f62000
	v_lshl_add_u64 v[20:21], v[20:21], 0, s[100:101]
	global_load_dwordx4 v[20:23], v[20:21], off offset:3072
	v_mul_f32_e32 v2, v56, v57
	v_exp_f32_e32 v50, v50
	v_exp_f32_e32 v51, v51
	v_rcp_f32_e32 v56, v2
	v_add_f32_e32 v2, 1.0, v64
	v_pk_add_f32 v[54:55], v[54:55], 1.0 op_sel_hi:[1,0]
	v_rcp_f32_e32 v61, v2
	v_mul_f32_e32 v2, v54, v55
	v_rcp_f32_e32 v57, v2
	v_add_f32_e32 v2, 1.0, v65
	v_pk_add_f32 v[58:59], v[58:59], 1.0 op_sel_hi:[1,0]
	v_rcp_f32_e32 v54, v2
	v_mul_f32_e32 v2, v58, v59
	v_rcp_f32_e32 v58, v2
	v_add_f32_e32 v2, 1.0, v62
	v_pk_add_f32 v[50:51], v[50:51], 1.0 op_sel_hi:[1,0]
	v_rcp_f32_e32 v55, v2
	v_mul_f32_e32 v2, v50, v51
	v_rcp_f32_e32 v59, v2
	s_waitcnt lgkmcnt(0)
	v_pk_mul_f32 v[46:47], v[46:47], v[48:49]
	v_pk_mul_f32 v[40:41], v[44:45], v[40:41]
	s_addk_i32 s38, 0x80
	v_pk_mul_f32 v[40:41], v[56:57], v[40:41]
	v_pk_mul_f32 v[44:45], v[58:59], v[46:47]
	v_pk_fma_f32 v[0:1], v[60:61], v[0:1], v[40:41]
	v_pk_fma_f32 v[42:43], v[54:55], v[42:43], v[44:45]
	v_cvt_pk_bf16_f32 v0, v0, v1
	v_cvt_pk_bf16_f32 v1, v42, v43
	global_store_dwordx2 v[68:69], v[0:1], off offset:96
	s_waitcnt lgkmcnt(0)
	s_barrier
	s_add_u32 s54, s54, 0x160000
	s_addc_u32 s55, s55, 0
	s_cmp_eq_u32 s54, 0x1600000
	s_cbranch_scc1 .LBB0_281

.LBB0_217:
	s_or_b64 exec, exec, s[6:7]
	s_waitcnt lgkmcnt(2)
	v_readlane_b32 s6, v255, 10
	v_and_b32_e32 v2, 1, v88
	v_lshrrev_b32_e32 v30, 1, v88
	v_or_b32_e32 v21, s6, v54
	v_lshlrev_b32_e32 v2, 5, v2
	v_lshl_or_b32 v2, v30, 4, v2
	v_add_u32_e32 v2, v56, v2
	v_add_u32_e32 v2, 0x1c00, v2
	s_add_u32 s6, s39, s54
	s_addc_u32 s7, s78, s55
	v_lshl_add_u64 v[22:23], s[6:7], 0, v[2:3]
	v_add_co_u32_e32 v22, vcc, s63, v22
	s_nop 1
	v_addc_co_u32_e32 v23, vcc, 0, v23, vcc
	s_waitcnt lgkmcnt(0)
	s_barrier
	global_load_dwordx4 v[238:241], v[22:23], off
	global_load_dwordx4 v[242:245], v[22:23], off offset:64
	global_load_dwordx4 v[246:249], v[22:23], off offset:2048
	global_load_dwordx4 v[250:253], v[22:23], off offset:2112
	global_load_dwordx4 v[154:157], v[22:23], off offset:-2048
	global_load_dwordx4 v[216:219], v[22:23], off offset:-1984
	v_mul_lo_u32 v20, v55, s60
	v_add_lshl_u32 v20, v21, v20, 1
	v_mov_b32_e32 v21, v3
	v_lshl_add_u64 v[20:21], s[6:7], 0, v[20:21]
	s_lshl_b32 s6, s41, 8
	s_add_i32 s6, s6, 0
	s_mov_b32 s101, 0
	v_cmp_lt_u32_e64 s[20:21], 1, v88
	v_cmp_eq_u32_e64 s[22:23], 3, v88
	v_add_u32_e32 v2, s6, v89
	v_add_u32_e32 v2, 0x20800, v2
	v_add_u32_e32 v32, 0x1f800, v89
	ds_read_b32 v36, v2
	ds_read_b32 v37, v2 offset:64
	ds_read_b32 v38, v2 offset:128
	ds_read_b32 v39, v2 offset:192
	v_add_u32_e32 v33, 64, v32
	v_add_u32_e32 v34, 0x80, v32
	v_add_u32_e32 v35, 0xc0, v32
	ds_read2st64_b32 v[160:161], v32 offset1:8
	ds_read2st64_b32 v[162:163], v33 offset1:8
	ds_read2st64_b32 v[164:165], v34 offset1:8
	ds_read2st64_b32 v[166:167], v35 offset1:8
	ds_read2st64_b32 v[168:169], v32 offset0:1 offset1:9
	ds_read2st64_b32 v[170:171], v33 offset0:1 offset1:9
	ds_read2st64_b32 v[172:173], v34 offset0:1 offset1:9
	ds_read2st64_b32 v[174:175], v35 offset0:1 offset1:9
	ds_read2st64_b32 v[176:177], v32 offset0:2 offset1:10
	ds_read2st64_b32 v[178:179], v33 offset0:2 offset1:10
	ds_read2st64_b32 v[180:181], v34 offset0:2 offset1:10
	ds_read2st64_b32 v[182:183], v35 offset0:2 offset1:10
	ds_read2st64_b32 v[184:185], v32 offset0:3 offset1:11
	ds_read2st64_b32 v[186:187], v33 offset0:3 offset1:11
	ds_read2st64_b32 v[188:189], v34 offset0:3 offset1:11
	ds_read2st64_b32 v[190:191], v35 offset0:3 offset1:11
	ds_read2st64_b32 v[192:193], v32 offset0:4 offset1:12
	ds_read2st64_b32 v[194:195], v33 offset0:4 offset1:12
	ds_read2st64_b32 v[196:197], v34 offset0:4 offset1:12
	ds_read2st64_b32 v[198:199], v35 offset0:4 offset1:12
	ds_read2st64_b32 v[200:201], v32 offset0:5 offset1:13
	ds_read2st64_b32 v[202:203], v33 offset0:5 offset1:13
	ds_read2st64_b32 v[204:205], v34 offset0:5 offset1:13
	ds_read2st64_b32 v[206:207], v35 offset0:5 offset1:13
	ds_read2st64_b32 v[208:209], v32 offset0:6 offset1:14
	ds_read2st64_b32 v[210:211], v33 offset0:6 offset1:14
	ds_read2st64_b32 v[212:213], v34 offset0:6 offset1:14
	ds_read2st64_b32 v[214:215], v35 offset0:6 offset1:14
	ds_read2_b32 v[220:221], v106 offset1:68
	ds_read2_b32 v[222:223], v106 offset0:136 offset1:204
	ds_read2_b32 v[224:225], v106 offset0:16 offset1:84
	ds_read2_b32 v[226:227], v106 offset0:152 offset1:220
	ds_read2_b32 v[230:231], v106 offset0:32 offset1:100
	ds_read2_b32 v[232:233], v106 offset0:168 offset1:236
	ds_read2_b32 v[234:235], v106 offset0:48 offset1:116
	ds_read2_b32 v[236:237], v106 offset0:184 offset1:252
	s_xor_b32 s96, s41, 1
	v_readlane_b32 s56, v255, 17
	v_readlane_b32 s57, v255, 18
	s_lshl_b32 s58, s96, 8
	s_add_i32 s58, s58, 0x20800
	v_add_u32_e32 v31, s58, v89
	s_and_b64 s[56:57], s[56:57], s[22:23]
	v_cndmask_b32_e64 v22, v136, 0, s[0:1]
	v_cndmask_b32_e64 v23, v122, 1.0, s[0:1]
	v_fmac_f32_e32 v132, v22, v123
	v_mul_f32_e32 v30, v23, v123
	v_cndmask_b32_e64 v22, v22, v132, s[20:21]
	v_cndmask_b32_e64 v23, v23, v30, s[20:21]
	v_fmac_f32_e32 v131, v22, v120
	v_mul_f32_e32 v30, v23, v120
	v_cndmask_b32_e64 v22, v22, v131, s[22:23]
	v_cndmask_b32_e64 v23, v23, v30, s[22:23]
	v_cndmask_b32_e64 v24, v130, 0, s[0:1]
	v_cndmask_b32_e64 v25, v126, 1.0, s[0:1]
	v_fmac_f32_e32 v129, v24, v128
	v_mul_f32_e32 v30, v25, v128
	v_cndmask_b32_e64 v24, v24, v129, s[20:21]
	v_cndmask_b32_e64 v25, v25, v30, s[20:21]
	v_fmac_f32_e32 v125, v24, v124
	v_mul_f32_e32 v30, v25, v124
	v_cndmask_b32_e64 v24, v24, v125, s[22:23]
	v_cndmask_b32_e64 v25, v25, v30, s[22:23]
	v_cndmask_b32_e64 v26, v139, 0, s[0:1]
	v_cndmask_b32_e64 v27, v135, 1.0, s[0:1]
	v_fmac_f32_e32 v138, v26, v137
	v_mul_f32_e32 v30, v27, v137
	v_cndmask_b32_e64 v26, v26, v138, s[20:21]
	v_cndmask_b32_e64 v27, v27, v30, s[20:21]
	v_fmac_f32_e32 v134, v26, v133
	v_mul_f32_e32 v30, v27, v133
	v_cndmask_b32_e64 v26, v26, v134, s[22:23]
	v_cndmask_b32_e64 v27, v27, v30, s[22:23]
	v_cndmask_b32_e64 v28, v146, 0, s[0:1]
	v_cndmask_b32_e64 v29, v142, 1.0, s[0:1]
	v_fmac_f32_e32 v145, v28, v143
	v_mul_f32_e32 v30, v29, v143
	v_cndmask_b32_e64 v28, v28, v145, s[20:21]
	v_cndmask_b32_e64 v29, v29, v30, s[20:21]
	v_fmac_f32_e32 v141, v28, v140
	v_mul_f32_e32 v30, v29, v140
	v_cndmask_b32_e64 v28, v28, v141, s[22:23]
	v_cndmask_b32_e64 v29, v29, v30, s[22:23]
	s_waitcnt lgkmcnt(15)
	s_andn2_b64 vcc, exec, s[82:83]
	s_cbranch_vccnz .Lb4_fold_done
	v_fma_f32 v36, v160, v36, v161
	v_fma_f32 v37, v162, v37, v163
	v_fma_f32 v38, v164, v38, v165
	v_fma_f32 v39, v166, v39, v167
	s_andn2_b64 vcc, exec, s[84:85]
	s_cbranch_vccnz .Lb4_fold_done
	v_fma_f32 v36, v168, v36, v169
	v_fma_f32 v37, v170, v37, v171
	v_fma_f32 v38, v172, v38, v173
	v_fma_f32 v39, v174, v39, v175
	s_andn2_b64 vcc, exec, s[86:87]
	s_cbranch_vccnz .Lb4_fold_done
	v_fma_f32 v36, v176, v36, v177
	v_fma_f32 v37, v178, v37, v179
	v_fma_f32 v38, v180, v38, v181
	v_fma_f32 v39, v182, v39, v183
	s_andn2_b64 vcc, exec, s[88:89]
	s_cbranch_vccnz .Lb4_fold_done
	v_fma_f32 v36, v184, v36, v185
	v_fma_f32 v37, v186, v37, v187
	v_fma_f32 v38, v188, v38, v189
	v_fma_f32 v39, v190, v39, v191
	s_andn2_b64 vcc, exec, s[90:91]
	s_cbranch_vccnz .Lb4_fold_done
	v_fma_f32 v36, v192, v36, v193
	v_fma_f32 v37, v194, v37, v195
	v_fma_f32 v38, v196, v38, v197
	v_fma_f32 v39, v198, v39, v199
	s_waitcnt lgkmcnt(8)
	s_andn2_b64 vcc, exec, s[92:93]
	s_cbranch_vccnz .Lb4_fold_done
	v_fma_f32 v36, v200, v36, v201
	v_fma_f32 v37, v202, v37, v203
	v_fma_f32 v38, v204, v38, v205
	v_fma_f32 v39, v206, v39, v207
	s_andn2_b64 vcc, exec, s[94:95]
	s_cbranch_vccnz .Lb4_fold_done
	v_fma_f32 v36, v208, v36, v209
	v_fma_f32 v37, v210, v37, v211
	v_fma_f32 v38, v212, v38, v213
	v_fma_f32 v39, v214, v39, v215
.Lb4_fold_done:
	v_fmac_f32_e32 v22, v23, v36
	v_fmac_f32_e32 v24, v25, v37
	v_fmac_f32_e32 v26, v27, v38
	v_fmac_f32_e32 v28, v29, v39
	s_waitcnt lgkmcnt(0)
	v_fma_f32 v220, v74, v22, v220
	v_fmac_f32_e32 v221, v75, v220
	v_fma_f32 v222, v0, v221, v222
	v_fmac_f32_e32 v223, v1, v222
	v_fma_f32 v224, v78, v24, v224
	v_fmac_f32_e32 v225, v79, v224
	v_fma_f32 v226, v76, v225, v226
	v_fmac_f32_e32 v227, v77, v226
	v_fma_f32 v230, v82, v26, v230
	v_fmac_f32_e32 v231, v83, v230
	v_fma_f32 v232, v80, v231, v232
	v_fmac_f32_e32 v233, v81, v232
	v_fma_f32 v234, v86, v28, v234
	v_fmac_f32_e32 v235, v87, v234
	v_fma_f32 v236, v84, v235, v236
	v_fmac_f32_e32 v237, v85, v236
	ds_write2_b32 v106, v220, v221 offset1:68
	ds_write2_b32 v106, v222, v223 offset0:136 offset1:204
	ds_write2_b32 v106, v224, v225 offset0:16 offset1:84
	ds_write2_b32 v106, v226, v227 offset0:152 offset1:220
	ds_write2_b32 v106, v230, v231 offset0:32 offset1:100
	ds_write2_b32 v106, v232, v233 offset0:168 offset1:236
	ds_write2_b32 v106, v234, v235 offset0:48 offset1:116
	ds_write2_b32 v106, v236, v237 offset0:184 offset1:252
	s_and_saveexec_b64 s[58:59], s[56:57]
	ds_write_b32 v31, v223
	ds_write_b32 v31, v227 offset:64
	ds_write_b32 v31, v233 offset:128
	ds_write_b32 v31, v237 offset:192
	s_or_b64 exec, exec, s[58:59]
	s_mov_b64 s[0:1], exec
	s_branch .LBB0_208
